# de-phase: WGs>=128 (14-tile WGs) start P1/P6 tile loops ~31us late so store bursts of the two halves do not coincide
# speedup vs baseline: 1.0157x; 1.0157x over previous
.LBB0_402:
	v_writelane_b32 v252, s14, 54
	v_writelane_b32 v252, s86, 56
	s_nop 1
	v_writelane_b32 v252, s87, 57
	v_writelane_b32 v252, s84, 58
	s_nop 1
	v_writelane_b32 v252, s85, 59
	v_writelane_b32 v252, s68, 60
	s_nop 1
	v_writelane_b32 v253, s72, 0
	v_writelane_b32 v252, s69, 61
	v_writelane_b32 v253, s73, 1
	v_writelane_b32 v252, s70, 62
	v_writelane_b32 v253, s74, 2
	v_writelane_b32 v252, s71, 63
	v_writelane_b32 v253, s75, 3
	s_or_b64 exec, exec, s[0:1]
	s_add_u32 s18, s76, 0xa000000
	s_addc_u32 s19, s77, 0
	s_cmpk_lt_i32 s26, 0xe80
	s_cselect_b64 s[0:1], -1, 0
	s_add_u32 s15, s76, 0x7800000
	s_addc_u32 s88, s77, 0
	v_writelane_b32 v253, s0, 4
	s_add_u32 s89, s76, 0x8000000
	s_addc_u32 s90, s77, 0
	v_writelane_b32 v253, s1, 5
	s_bfe_u32 s0, s82, 0x20006
	s_lshr_b32 s1, s82, 8
	s_cmp_eq_u32 s1, 1
	s_cselect_b64 s[10:11], -1, 0
	s_lshl_b32 s2, s1, 6
	s_lshl_b32 s17, s1, 13
	s_or_b32 s1, s2, 16
	v_writelane_b32 v253, s1, 6
	s_lshl_b32 s65, s1, 7
	s_or_b32 s1, s2, 32
	v_writelane_b32 v253, s1, 7
	s_lshl_b32 s1, s1, 7
	v_writelane_b32 v253, s1, 8
	v_writelane_b32 v253, s2, 10
	s_or_b32 s1, s2, 48
	v_writelane_b32 v253, s1, 11
	s_lshl_b32 s1, s1, 7
	s_lshl_b32 s64, s0, 12
	v_writelane_b32 v253, s1, 12
	s_mov_b32 s2, s82
	v_writelane_b32 v253, s2, 14
	s_cmpk_lt_u32 s82, 0x100
	v_cndmask_b32_e64 v192, 0, 1, s[10:11]
	v_writelane_b32 v253, s3, 15
	s_cselect_b64 s[2:3], -1, 0
	v_writelane_b32 v253, s2, 16
	s_lshl_b32 s0, s0, 5
	s_barrier
	v_writelane_b32 v253, s3, 17
	v_writelane_b32 v253, s0, 18
	s_add_u32 s0, s76, 0x12000000
	s_addc_u32 s1, s77, 0
	v_writelane_b32 v253, s0, 19
	s_cmpk_gt_i32 s26, 0xe7f
	s_nop 0
	v_writelane_b32 v253, s1, 20
	s_mov_b32 s0, s26
	v_writelane_b32 v253, s0, 21
	s_mov_b32 s26, s80
	s_nop 0
	v_writelane_b32 v253, s1, 22
	v_writelane_b32 v253, s27, 23
	s_cbranch_scc1 .LBB0_549
	s_add_u32 s91, s76, 0x5800000
	v_readlane_b32 s0, v253, 8
	s_addc_u32 s92, s77, 0
	s_add_i32 s96, s0, 0
	v_readlane_b32 s0, v253, 12
	s_add_i32 s25, s64, 0
	s_add_i32 s97, s0, 0
	v_readlane_b32 s0, v253, 21
	s_mov_b32 s23, 0
	s_add_i32 s93, s25, 0x10000
	s_add_i32 s94, s17, 0
	s_add_i32 s95, s65, 0
	s_add_i32 s12, s25, 0x14000
	s_add_i32 s13, s25, 0x18000
	s_add_i32 s25, s25, 0x1c000
	s_add_i32 s33, s0, 0xfffff200
	s_lshl_b32 s84, s0, 8
	s_lshl_b32 s85, s80, 8
	s_mov_b64 s[44:45], 0x80
	s_mov_b64 s[46:47], 0x5800080
	s_mov_b64 s[48:49], 0x4900100
	s_mov_b64 s[50:51], 0x5800100
	s_mov_b64 s[52:53], 0x4980100
	s_mov_b64 s[54:55], 0x4900180
	s_mov_b64 s[56:57], 0x5800180
	s_mov_b64 s[58:59], 0x4980180
	s_mov_b64 s[60:61], 0x100
	s_mov_b64 s[62:63], 0xf80
	v_mov_b32_e32 v129, 0
	s_mov_b64 s[66:67], 0xa000080
	s_mov_b64 s[68:69], 0xa000100
	s_mov_b64 s[70:71], 0x80100
	s_mov_b64 s[72:73], 0x180
	s_mov_b64 s[74:75], 0xa000180
	s_mov_b64 s[8:9], 0x80180
	s_movk_i32 s86, 0x3800
	v_mov_b32_e32 v146, 1
	v_mov_b32_e32 v147, 0x1000
	v_mov_b32_e32 v148, 0x2000
	v_mov_b32_e32 v149, 0x3000
	v_readlane_b32 s87, v252, 54
	s_mov_b32 s40, s0
	v_readlane_b32 s1, v253, 22
	s_cmpk_lt_u32 s40, 0x80
	s_cbranch_scc1 .Lp1_nodelay
	s_mov_b32 s98, 8
.Lp1_delay:
	s_sleep 127
	s_sub_u32 s98, s98, 1
	s_cmp_lg_u32 s98, 0
	s_cbranch_scc1 .Lp1_delay
.Lp1_nodelay:
	s_branch .LBB0_406

.LBB0_627:
	s_add_u32 s0, s76, 0x2e000000
	s_addc_u32 s1, s77, 0
	v_writelane_b32 v253, s0, 40
	s_add_u32 s2, s76, 0x22000000
	s_addc_u32 s3, s77, 0
	v_writelane_b32 v253, s1, 41
	s_nop 0
	v_readlane_b32 s0, v253, 4
	v_readlane_b32 s1, v253, 5
	s_andn2_b64 vcc, exec, s[0:1]
	s_barrier
	s_cbranch_vccnz .LBB0_691
	v_readlane_b32 s0, v253, 28
	s_add_i32 s57, s0, 0
	v_readlane_b32 s0, v253, 30
	s_add_i32 s58, s0, 0
	v_readlane_b32 s0, v253, 8
	s_add_i32 s63, s64, 0
	s_add_i32 s59, s0, 0
	v_readlane_b32 s0, v253, 12
	s_mov_b32 s9, 0
	s_add_i32 s56, s63, 0x10000
	s_add_i32 s60, s0, 0
	s_add_i32 s61, s63, 0x14000
	s_add_i32 s62, s63, 0x18000
	s_add_i32 s63, s63, 0x1c000
	s_add_i32 s66, s78, 0xfffffa00
	s_lshl_b32 s67, s78, 8
	s_lshl_b32 s68, s80, 8
	s_add_i32 s69, 0, 0x10000
	s_add_i32 s70, 0, 0x14000
	s_mov_b64 s[12:13], 0x80
	s_mov_b64 s[14:15], 0x12000080
	s_mov_b64 s[16:17], 0x3000100
	s_mov_b64 s[18:19], 0x12000100
	s_mov_b64 s[20:21], 0x3080100
	s_mov_b64 s[22:23], 0x3000180
	s_mov_b64 s[36:37], 0x12000180
	s_mov_b64 s[38:39], 0x3080180
	s_mov_b64 s[40:41], 0x100
	s_mov_b64 s[42:43], 0xf80
	s_movk_i32 s71, 0x1080
	s_movk_i32 s72, 0x2100
	s_mov_b64 s[44:45], 0x2400100
	s_mov_b64 s[46:47], 0x2480100
	s_mov_b64 s[48:49], 0x2400180
	s_mov_b64 s[50:51], 0x2480180
	s_movk_i32 s73, 0x1800
	v_mov_b32_e32 v129, 0
	v_mov_b32_e32 v146, 1
	s_mov_b32 s74, s78
	s_mov_b32 s75, s78
	s_cmpk_lt_u32 s75, 0x80
	s_cbranch_scc1 .Lp6_nodelay
	s_mov_b32 s98, 8

	.amdhsa_kernel _Z4mega6Params
		.amdhsa_group_segment_fixed_size 0
		.amdhsa_private_segment_fixed_size 0
		.amdhsa_kernarg_size 488
		.amdhsa_user_sgpr_count 2
		.amdhsa_user_sgpr_dispatch_ptr 0
		.amdhsa_user_sgpr_queue_ptr 0
		.amdhsa_user_sgpr_kernarg_segment_ptr 1
		.amdhsa_user_sgpr_dispatch_id 0
		.amdhsa_user_sgpr_kernarg_preload_length 0
		.amdhsa_user_sgpr_kernarg_preload_offset 0
		.amdhsa_user_sgpr_private_segment_size 0
		.amdhsa_uses_dynamic_stack 0
		.amdhsa_enable_private_segment 0
		.amdhsa_system_sgpr_workgroup_id_x 1
		.amdhsa_system_sgpr_workgroup_id_y 0
		.amdhsa_system_sgpr_workgroup_id_z 0
		.amdhsa_system_sgpr_workgroup_info 0
		.amdhsa_system_vgpr_workitem_id 2
		.amdhsa_next_free_vgpr 256
		.amdhsa_next_free_sgpr 102
		.amdhsa_accum_offset 256
		.amdhsa_reserve_vcc 1
		.amdhsa_float_round_mode_32 0
		.amdhsa_float_round_mode_16_64 0
		.amdhsa_float_denorm_mode_32 3
		.amdhsa_float_denorm_mode_16_64 3
		.amdhsa_dx10_clamp 1
		.amdhsa_ieee_mode 1
		.amdhsa_fp16_overflow 0
		.amdhsa_tg_split 0
		.amdhsa_exception_fp_ieee_invalid_op 0
		.amdhsa_exception_fp_denorm_src 0
		.amdhsa_exception_fp_ieee_div_zero 0
		.amdhsa_exception_fp_ieee_overflow 0
		.amdhsa_exception_fp_ieee_underflow 0
		.amdhsa_exception_fp_ieee_inexact 0
		.amdhsa_exception_int_div_zero 0
	.end_amdhsa_kernel

amdhsa.kernels:
  - .agpr_count:     0
    .args:
      - .offset:         0
        .size:           232
        .value_kind:     by_value
      - .offset:         232
        .size:           4
        .value_kind:     hidden_block_count_x
      - .offset:         236
        .size:           4
        .value_kind:     hidden_block_count_y
      - .offset:         240
        .size:           4
        .value_kind:     hidden_block_count_z
      - .offset:         244
        .size:           2
        .value_kind:     hidden_group_size_x
      - .offset:         246
        .size:           2
        .value_kind:     hidden_group_size_y
      - .offset:         248
        .size:           2
        .value_kind:     hidden_group_size_z
      - .offset:         250
        .size:           2
        .value_kind:     hidden_remainder_x
      - .offset:         252
        .size:           2
        .value_kind:     hidden_remainder_y
      - .offset:         254
        .size:           2
        .value_kind:     hidden_remainder_z
      - .offset:         272
        .size:           8
        .value_kind:     hidden_global_offset_x
      - .offset:         280
        .size:           8
        .value_kind:     hidden_global_offset_y
      - .offset:         288
        .size:           8
        .value_kind:     hidden_global_offset_z
      - .offset:         296
        .size:           2
        .value_kind:     hidden_grid_dims
      - .offset:         320
        .size:           8
        .value_kind:     hidden_multigrid_sync_arg
      - .offset:         352
        .size:           4
        .value_kind:     hidden_dynamic_lds_size
    .group_segment_fixed_size: 0
    .kernarg_segment_align: 8
    .kernarg_segment_size: 488
    .language:       OpenCL C
    .language_version:
      - 2
      - 0
    .max_flat_workgroup_size: 512
    .name:           _Z4mega6Params
    .private_segment_fixed_size: 0
    .sgpr_count:     108
    .sgpr_spill_count: 270
    .symbol:         _Z4mega6Params.kd
    .uniform_work_group_size: 1
    .uses_dynamic_stack: false
    .vgpr_count:     256
    .vgpr_spill_count: 0
    .wavefront_size: 64
